# cross-attention items (phase 8): K/V staging loads batched with counted waits (sample item 32 loads, prompt item 16 loads) and prompt Q partial-sum loads issued before the LDS staging
# speedup vs baseline: 1.1658x; 1.0116x over previous
.LBB0_1805:
	s_cmpk_gt_i32 s10, 0xff
	s_cbranch_scc0 .LBB0_1810
	s_add_i32 s6, s10, 0xffffff00
	v_mov_b32_e32 v50, v230
	s_lshl_b32 s7, s10, 7
	s_lshr_b32 s12, s6, 2
	s_and_b32 s11, s7, 0x180
	v_and_b32_e32 v3, 31, v50
	v_mov_b32_e32 v6, s23
	s_movk_i32 s7, 0x840
	s_lshl_b32 s6, s12, 8
	v_lshlrev_b32_e32 v48, 4, v3
	v_lshl_add_u32 v2, v3, 3, 0
	v_mad_u32_u24 v6, v3, s7, v6
	v_ashrrev_i32_e32 v3, 5, v50
	v_add_u32_e32 v8, s6, v3
	v_readlane_b32 s44, v253, 21
	v_ashrrev_i32_e32 v9, 31, v8
	v_readlane_b32 s58, v253, 35
	v_readlane_b32 s59, v253, 36
	v_lshlrev_b64 v[12:13], 11, v[8:9]
	s_lshl_b32 s90, s11, 2
	v_lshl_add_u64 v[4:5], s[58:59], 0, v[48:49]
	v_or_b32_e32 v12, s90, v12
	v_lshl_add_u64 v[8:9], v[4:5], 0, v[12:13]
	s_waitcnt vmcnt(0) lgkmcnt(0)
	s_barrier
	global_load_dwordx4 v[112:115], v[8:9], off
	v_readlane_b32 s45, v253, 22
	v_readlane_b32 s46, v253, 23
	v_readlane_b32 s47, v253, 24
	v_readlane_b32 s48, v253, 25
	v_readlane_b32 s49, v253, 26
	v_readlane_b32 s50, v253, 27
	v_readlane_b32 s51, v253, 28
	v_readlane_b32 s52, v253, 29
	v_readlane_b32 s53, v253, 30
	v_readlane_b32 s54, v253, 31
	v_readlane_b32 s55, v253, 32
	v_readlane_b32 s56, v253, 33
	v_readlane_b32 s57, v253, 34
	v_readlane_b32 s44, v253, 37
	v_readlane_b32 s45, v253, 38
	v_readlane_b32 s46, v253, 39
	v_readlane_b32 s47, v253, 40
	v_readlane_b32 s48, v253, 41
	v_readlane_b32 s49, v253, 42
	v_readlane_b32 s50, v253, 43
	v_readlane_b32 s51, v253, 44
	v_readlane_b32 s52, v253, 45
	v_readlane_b32 s53, v253, 46
	v_readlane_b32 s54, v253, 47
	v_readlane_b32 s55, v253, 48
	v_readlane_b32 s56, v253, 49
	v_readlane_b32 s57, v253, 50
	v_readlane_b32 s58, v253, 51
	v_readlane_b32 s59, v253, 52
	s_mov_b64 s[100:101], 0x8000
	v_lshl_add_u64 v[0:1], s[44:45], 0, v[48:49]
	v_lshl_add_u64 v[0:1], v[0:1], 0, v[12:13]
	global_load_dwordx4 v[176:179], v[0:1], off
	v_lshl_add_u64 v[8:9], v[8:9], 0, s[100:101]
	global_load_dwordx4 v[116:119], v[8:9], off
	v_lshl_add_u64 v[0:1], v[0:1], 0, s[100:101]
	global_load_dwordx4 v[180:183], v[0:1], off
	v_lshl_add_u64 v[8:9], v[8:9], 0, s[100:101]
	global_load_dwordx4 v[120:123], v[8:9], off
	v_lshl_add_u64 v[0:1], v[0:1], 0, s[100:101]
	global_load_dwordx4 v[184:187], v[0:1], off
	v_lshl_add_u64 v[8:9], v[8:9], 0, s[100:101]
	global_load_dwordx4 v[124:127], v[8:9], off
	v_lshl_add_u64 v[0:1], v[0:1], 0, s[100:101]
	global_load_dwordx4 v[188:191], v[0:1], off
	v_lshl_add_u64 v[8:9], v[8:9], 0, s[100:101]
	global_load_dwordx4 v[128:131], v[8:9], off
	v_lshl_add_u64 v[0:1], v[0:1], 0, s[100:101]
	global_load_dwordx4 v[192:195], v[0:1], off
	v_lshl_add_u64 v[8:9], v[8:9], 0, s[100:101]
	global_load_dwordx4 v[132:135], v[8:9], off
	v_lshl_add_u64 v[0:1], v[0:1], 0, s[100:101]
	global_load_dwordx4 v[196:199], v[0:1], off
	v_lshl_add_u64 v[8:9], v[8:9], 0, s[100:101]
	global_load_dwordx4 v[136:139], v[8:9], off
	v_lshl_add_u64 v[0:1], v[0:1], 0, s[100:101]
	global_load_dwordx4 v[200:203], v[0:1], off
	v_lshl_add_u64 v[8:9], v[8:9], 0, s[100:101]
	global_load_dwordx4 v[140:143], v[8:9], off
	v_lshl_add_u64 v[0:1], v[0:1], 0, s[100:101]
	global_load_dwordx4 v[204:207], v[0:1], off
	v_lshl_add_u64 v[8:9], v[8:9], 0, s[100:101]
	global_load_dwordx4 v[144:147], v[8:9], off
	v_lshl_add_u64 v[0:1], v[0:1], 0, s[100:101]
	global_load_dwordx4 v[208:211], v[0:1], off
	v_lshl_add_u64 v[8:9], v[8:9], 0, s[100:101]
	global_load_dwordx4 v[148:151], v[8:9], off
	v_lshl_add_u64 v[0:1], v[0:1], 0, s[100:101]
	global_load_dwordx4 v[212:215], v[0:1], off
	v_lshl_add_u64 v[8:9], v[8:9], 0, s[100:101]
	global_load_dwordx4 v[152:155], v[8:9], off
	v_lshl_add_u64 v[0:1], v[0:1], 0, s[100:101]
	global_load_dwordx4 v[216:219], v[0:1], off
	v_lshl_add_u64 v[8:9], v[8:9], 0, s[100:101]
	global_load_dwordx4 v[156:159], v[8:9], off
	v_lshl_add_u64 v[0:1], v[0:1], 0, s[100:101]
	global_load_dwordx4 v[220:223], v[0:1], off
	v_lshl_add_u64 v[8:9], v[8:9], 0, s[100:101]
	global_load_dwordx4 v[160:163], v[8:9], off
	v_lshl_add_u64 v[0:1], v[0:1], 0, s[100:101]
	global_load_dwordx4 v[224:227], v[0:1], off
	v_lshl_add_u64 v[8:9], v[8:9], 0, s[100:101]
	global_load_dwordx4 v[164:167], v[8:9], off
	v_lshl_add_u64 v[0:1], v[0:1], 0, s[100:101]
	global_load_dwordx4 v[232:235], v[0:1], off
	v_lshl_add_u64 v[8:9], v[8:9], 0, s[100:101]
	global_load_dwordx4 v[168:171], v[8:9], off
	v_lshl_add_u64 v[0:1], v[0:1], 0, s[100:101]
	global_load_dwordx4 v[236:239], v[0:1], off
	v_lshl_add_u64 v[8:9], v[8:9], 0, s[100:101]
	global_load_dwordx4 v[172:175], v[8:9], off
	v_lshl_add_u64 v[0:1], v[0:1], 0, s[100:101]
	global_load_dwordx4 v[240:243], v[0:1], off
	v_mad_u32_u24 v10, v3, s24, v2
	v_lshl_add_u32 v7, v3, 1, v6
	s_waitcnt vmcnt(31)
	v_cvt_pk_bf16_f32 v16, v112, v113
	v_cvt_pk_bf16_f32 v17, v114, v115
	ds_write_b64 v10, v[16:17]
	s_waitcnt vmcnt(30)
	v_cvt_pk_bf16_f32 v18, v176, v177
	v_cvt_pk_bf16_f32 v19, v178, v179
	ds_write_b16 v7, v18
	ds_write_b16_d16_hi v7, v18 offset:528
	ds_write_b16 v7, v19 offset:1056
	ds_write_b16_d16_hi v7, v19 offset:1584
	s_waitcnt vmcnt(29)
	v_cvt_pk_bf16_f32 v16, v116, v117
	v_cvt_pk_bf16_f32 v17, v118, v119
	ds_write_b64 v10, v[16:17] offset:4352
	s_waitcnt vmcnt(28)
	v_cvt_pk_bf16_f32 v18, v180, v181
	v_cvt_pk_bf16_f32 v19, v182, v183
	ds_write_b16 v7, v18 offset:32
	ds_write_b16_d16_hi v7, v18 offset:560
	ds_write_b16 v7, v19 offset:1088
	ds_write_b16_d16_hi v7, v19 offset:1616
	s_waitcnt vmcnt(27)
	v_cvt_pk_bf16_f32 v16, v120, v121
	v_cvt_pk_bf16_f32 v17, v122, v123
	ds_write_b64 v10, v[16:17] offset:8704
	s_waitcnt vmcnt(26)
	v_cvt_pk_bf16_f32 v18, v184, v185
	v_cvt_pk_bf16_f32 v19, v186, v187
	ds_write_b16 v7, v18 offset:64
	ds_write_b16_d16_hi v7, v18 offset:592
	ds_write_b16 v7, v19 offset:1120
	ds_write_b16_d16_hi v7, v19 offset:1648
	s_waitcnt vmcnt(25)
	v_cvt_pk_bf16_f32 v16, v124, v125
	v_cvt_pk_bf16_f32 v17, v126, v127
	ds_write_b64 v10, v[16:17] offset:13056
	s_waitcnt vmcnt(24)
	v_cvt_pk_bf16_f32 v18, v188, v189
	v_cvt_pk_bf16_f32 v19, v190, v191
	ds_write_b16 v7, v18 offset:96
	ds_write_b16_d16_hi v7, v18 offset:624
	ds_write_b16 v7, v19 offset:1152
	ds_write_b16_d16_hi v7, v19 offset:1680
	s_waitcnt vmcnt(23)
	v_cvt_pk_bf16_f32 v16, v128, v129
	v_cvt_pk_bf16_f32 v17, v130, v131
	ds_write_b64 v10, v[16:17] offset:17408
	s_waitcnt vmcnt(22)
	v_cvt_pk_bf16_f32 v18, v192, v193
	v_cvt_pk_bf16_f32 v19, v194, v195
	ds_write_b16 v7, v18 offset:128
	ds_write_b16_d16_hi v7, v18 offset:656
	ds_write_b16 v7, v19 offset:1184
	ds_write_b16_d16_hi v7, v19 offset:1712
	s_waitcnt vmcnt(21)
	v_cvt_pk_bf16_f32 v16, v132, v133
	v_cvt_pk_bf16_f32 v17, v134, v135
	ds_write_b64 v10, v[16:17] offset:21760
	s_waitcnt vmcnt(20)
	v_cvt_pk_bf16_f32 v18, v196, v197
	v_cvt_pk_bf16_f32 v19, v198, v199
	ds_write_b16 v7, v18 offset:160
	ds_write_b16_d16_hi v7, v18 offset:688
	ds_write_b16 v7, v19 offset:1216
	ds_write_b16_d16_hi v7, v19 offset:1744
	s_waitcnt vmcnt(19)
	v_cvt_pk_bf16_f32 v16, v136, v137
	v_cvt_pk_bf16_f32 v17, v138, v139
	ds_write_b64 v10, v[16:17] offset:26112
	s_waitcnt vmcnt(18)
	v_cvt_pk_bf16_f32 v18, v200, v201
	v_cvt_pk_bf16_f32 v19, v202, v203
	ds_write_b16 v7, v18 offset:192
	ds_write_b16_d16_hi v7, v18 offset:720
	ds_write_b16 v7, v19 offset:1248
	ds_write_b16_d16_hi v7, v19 offset:1776
	s_waitcnt vmcnt(17)
	v_cvt_pk_bf16_f32 v16, v140, v141
	v_cvt_pk_bf16_f32 v17, v142, v143
	ds_write_b64 v10, v[16:17] offset:30464
	s_waitcnt vmcnt(16)
	v_cvt_pk_bf16_f32 v18, v204, v205
	v_cvt_pk_bf16_f32 v19, v206, v207
	ds_write_b16 v7, v18 offset:224
	ds_write_b16_d16_hi v7, v18 offset:752
	ds_write_b16 v7, v19 offset:1280
	ds_write_b16_d16_hi v7, v19 offset:1808
	s_waitcnt vmcnt(15)
	v_cvt_pk_bf16_f32 v16, v144, v145
	v_cvt_pk_bf16_f32 v17, v146, v147
	ds_write_b64 v10, v[16:17] offset:34816
	s_waitcnt vmcnt(14)
	v_cvt_pk_bf16_f32 v18, v208, v209
	v_cvt_pk_bf16_f32 v19, v210, v211
	ds_write_b16 v7, v18 offset:256
	ds_write_b16_d16_hi v7, v18 offset:784
	ds_write_b16 v7, v19 offset:1312
	ds_write_b16_d16_hi v7, v19 offset:1840
	s_waitcnt vmcnt(13)
	v_cvt_pk_bf16_f32 v16, v148, v149
	v_cvt_pk_bf16_f32 v17, v150, v151
	ds_write_b64 v10, v[16:17] offset:39168
	s_waitcnt vmcnt(12)
	v_cvt_pk_bf16_f32 v18, v212, v213
	v_cvt_pk_bf16_f32 v19, v214, v215
	ds_write_b16 v7, v18 offset:288
	ds_write_b16_d16_hi v7, v18 offset:816
	ds_write_b16 v7, v19 offset:1344
	ds_write_b16_d16_hi v7, v19 offset:1872
	s_waitcnt vmcnt(11)
	v_cvt_pk_bf16_f32 v16, v152, v153
	v_cvt_pk_bf16_f32 v17, v154, v155
	ds_write_b64 v10, v[16:17] offset:43520
	s_waitcnt vmcnt(10)
	v_cvt_pk_bf16_f32 v18, v216, v217
	v_cvt_pk_bf16_f32 v19, v218, v219
	ds_write_b16 v7, v18 offset:320
	ds_write_b16_d16_hi v7, v18 offset:848
	ds_write_b16 v7, v19 offset:1376
	ds_write_b16_d16_hi v7, v19 offset:1904
	s_waitcnt vmcnt(9)
	v_cvt_pk_bf16_f32 v16, v156, v157
	v_cvt_pk_bf16_f32 v17, v158, v159
	ds_write_b64 v10, v[16:17] offset:47872
	s_waitcnt vmcnt(8)
	v_cvt_pk_bf16_f32 v18, v220, v221
	v_cvt_pk_bf16_f32 v19, v222, v223
	ds_write_b16 v7, v18 offset:352
	ds_write_b16_d16_hi v7, v18 offset:880
	ds_write_b16 v7, v19 offset:1408
	ds_write_b16_d16_hi v7, v19 offset:1936
	s_waitcnt vmcnt(7)
	v_cvt_pk_bf16_f32 v16, v160, v161
	v_cvt_pk_bf16_f32 v17, v162, v163
	ds_write_b64 v10, v[16:17] offset:52224
	s_waitcnt vmcnt(6)
	v_cvt_pk_bf16_f32 v18, v224, v225
	v_cvt_pk_bf16_f32 v19, v226, v227
	ds_write_b16 v7, v18 offset:384
	ds_write_b16_d16_hi v7, v18 offset:912
	ds_write_b16 v7, v19 offset:1440
	ds_write_b16_d16_hi v7, v19 offset:1968
	s_waitcnt vmcnt(5)
	v_cvt_pk_bf16_f32 v16, v164, v165
	v_cvt_pk_bf16_f32 v17, v166, v167
	ds_write_b64 v10, v[16:17] offset:56576
	s_waitcnt vmcnt(4)
	v_cvt_pk_bf16_f32 v18, v232, v233
	v_cvt_pk_bf16_f32 v19, v234, v235
	ds_write_b16 v7, v18 offset:416
	ds_write_b16_d16_hi v7, v18 offset:944
	ds_write_b16 v7, v19 offset:1472
	ds_write_b16_d16_hi v7, v19 offset:2000
	s_waitcnt vmcnt(3)
	v_cvt_pk_bf16_f32 v16, v168, v169
	v_cvt_pk_bf16_f32 v17, v170, v171
	ds_write_b64 v10, v[16:17] offset:60928
	s_waitcnt vmcnt(2)
	v_cvt_pk_bf16_f32 v18, v236, v237
	v_cvt_pk_bf16_f32 v19, v238, v239
	ds_write_b16 v7, v18 offset:448
	ds_write_b16_d16_hi v7, v18 offset:976
	ds_write_b16 v7, v19 offset:1504
	ds_write_b16_d16_hi v7, v19 offset:2032
	s_waitcnt vmcnt(1)
	v_cvt_pk_bf16_f32 v16, v172, v173
	v_cvt_pk_bf16_f32 v17, v174, v175
	ds_write_b64 v10, v[16:17] offset:65280
	s_waitcnt vmcnt(0)
	v_cvt_pk_bf16_f32 v18, v240, v241
	v_cvt_pk_bf16_f32 v19, v242, v243
	ds_write_b16 v7, v18 offset:480
	ds_write_b16_d16_hi v7, v18 offset:1008
	ds_write_b16 v7, v19 offset:1536
	ds_write_b16_d16_hi v7, v19 offset:2064
	v_readfirstlane_b32 s8, v50
	s_cmp_lt_u32 s8, 64
	s_mov_b64 s[8:9], 0
	s_mov_b64 s[6:7], 0
	s_waitcnt lgkmcnt(0)
	s_barrier
	s_cbranch_scc0 .LBB0_1811
	s_lshl_b32 s8, s12, 13
	v_and_b32_e32 v29, 15, v50
	s_add_i32 s8, s8, 0x400000
	v_lshl_or_b32 v48, v29, 9, s8
	v_bfe_u32 v54, v50, 4, 2
	v_lshl_add_u64 v[0:1], v[48:49], 2, s[84:85]
	v_lshl_add_u64 v[0:1], v[0:1], 0, s[90:91]
	v_lshlrev_b32_e32 v2, 5, v54
	v_mov_b32_e32 v3, v49
	v_lshl_add_u64 v[24:25], v[0:1], 0, v[2:3]
	v_add_co_u32_e32 v26, vcc, s25, v24
	v_lshl_add_u64 v[12:13], v[24:25], 0, s[92:93]
	s_nop 0
	v_addc_co_u32_e32 v27, vcc, 0, v25, vcc
	global_load_dwordx4 v[0:3], v[24:25], off offset:16
	global_load_dwordx4 v[4:7], v[24:25], off
	global_load_dwordx4 v[8:11], v[26:27], off
	s_nop 0
	global_load_dwordx4 v[12:15], v[12:13], off offset:16
	v_lshl_add_u64 v[16:17], v[24:25], 0, s[94:95]
	v_lshl_add_u64 v[20:21], v[24:25], 0, s[2:3]
	v_and_b32_e32 v28, 63, v50
	v_mov_b32_e32 v60, 0
	v_mov_b32_e32 v62, 0xff800000
	s_mov_b32 s8, 4
	v_mov_b32_e32 v44, 0
	v_mov_b32_e32 v45, v60
	v_mov_b32_e32 v46, v60
	v_mov_b32_e32 v47, v60
	v_mov_b32_e32 v40, 0
	v_mov_b32_e32 v41, v60
	v_mov_b32_e32 v42, v60
	v_mov_b32_e32 v43, v60
	v_mov_b32_e32 v36, 0
	v_mov_b32_e32 v37, v60
	v_mov_b32_e32 v38, v60
	v_mov_b32_e32 v39, v60
	v_mov_b32_e32 v30, v60
	v_mov_b32_e32 v31, v60
	v_mov_b32_e32 v32, 0
	v_mov_b32_e32 v33, v60
	v_mov_b32_e32 v34, v60
	v_mov_b32_e32 v35, v60
	s_waitcnt vmcnt(1)
	v_pk_add_f32 v[6:7], v[6:7], v[10:11]
	v_pk_add_f32 v[4:5], v[4:5], v[8:9]
	s_waitcnt vmcnt(0)
	v_pk_add_f32 v[8:9], v[2:3], v[14:15]
	v_pk_add_f32 v[2:3], v[0:1], v[12:13]
	v_cvt_pk_bf16_f32 v0, v4, v5
	v_cvt_pk_bf16_f32 v1, v6, v7
	v_cvt_pk_bf16_f32 v2, v2, v3
	v_cvt_pk_bf16_f32 v3, v8, v9
	global_load_dwordx4 v[4:7], v[24:25], off offset:144
	global_load_dwordx4 v[8:11], v[24:25], off offset:128
	global_load_dwordx4 v[12:15], v[26:27], off offset:128
	s_nop 0
	global_load_dwordx4 v[16:19], v[16:17], off offset:16
	s_waitcnt vmcnt(1)
	v_pk_add_f32 v[10:11], v[10:11], v[14:15]
	v_pk_add_f32 v[8:9], v[8:9], v[12:13]
	s_waitcnt vmcnt(0)
	v_pk_add_f32 v[12:13], v[6:7], v[18:19]
	v_pk_add_f32 v[6:7], v[4:5], v[16:17]
	v_cvt_pk_bf16_f32 v4, v8, v9
	v_cvt_pk_bf16_f32 v5, v10, v11
	v_cvt_pk_bf16_f32 v6, v6, v7
	v_cvt_pk_bf16_f32 v7, v12, v13
	global_load_dwordx4 v[8:11], v[24:25], off offset:272
	global_load_dwordx4 v[12:15], v[24:25], off offset:256
	global_load_dwordx4 v[16:19], v[26:27], off offset:256
	s_nop 0
	global_load_dwordx4 v[20:23], v[20:21], off offset:16
	s_waitcnt vmcnt(1)
	v_pk_add_f32 v[14:15], v[14:15], v[18:19]
	v_pk_add_f32 v[12:13], v[12:13], v[16:17]
	s_waitcnt vmcnt(0)
	v_pk_add_f32 v[16:17], v[10:11], v[22:23]
	v_pk_add_f32 v[10:11], v[8:9], v[20:21]
	v_cvt_pk_bf16_f32 v8, v12, v13
	v_cvt_pk_bf16_f32 v9, v14, v15
	v_cvt_pk_bf16_f32 v10, v10, v11
	v_cvt_pk_bf16_f32 v11, v16, v17
	global_load_dwordx4 v[12:15], v[24:25], off offset:400
	global_load_dwordx4 v[16:19], v[24:25], off offset:384
	v_lshl_add_u64 v[24:25], v[24:25], 0, s[4:5]
	global_load_dwordx4 v[20:23], v[26:27], off offset:384
	s_nop 0
	global_load_dwordx4 v[24:27], v[24:25], off offset:16
	s_waitcnt vmcnt(1)
	v_pk_add_f32 v[18:19], v[18:19], v[22:23]
	v_pk_add_f32 v[16:17], v[16:17], v[20:21]
	s_waitcnt vmcnt(0)
	v_pk_add_f32 v[14:15], v[14:15], v[26:27]
	v_cvt_pk_bf16_f32 v16, v16, v17
	v_cvt_pk_bf16_f32 v17, v18, v19
	v_cvt_pk_bf16_f32 v19, v14, v15
	v_and_b32_e32 v15, 64, v53
	v_xor_b32_e32 v14, 16, v53
	v_add_u32_e32 v15, 64, v15
	v_cmp_lt_i32_e32 vcc, v14, v15
	v_pk_add_f32 v[12:13], v[12:13], v[24:25]
	v_mov_b32_e32 v24, 0
	v_cndmask_b32_e32 v14, v53, v14, vcc
	v_lshlrev_b32_e32 v51, 2, v14
	v_xor_b32_e32 v14, 32, v53
	v_cmp_lt_i32_e32 vcc, v14, v15
	v_cvt_pk_bf16_f32 v18, v12, v13
	v_and_b32_e32 v12, 48, v50
	v_cndmask_b32_e32 v14, v53, v14, vcc
	v_lshlrev_b32_e32 v55, 2, v14
	v_lshrrev_b32_e32 v14, 1, v50
	v_or_b32_e32 v13, 48, v28
	v_and_b32_e32 v14, 24, v14
	v_or_b32_e32 v15, 0x70, v28
	v_mad_u32_u24 v50, v15, s26, v14
	v_mad_u32_u24 v56, v13, s26, v14
	v_mad_u32_u24 v57, v29, s26, v14
	v_mad_u32_u24 v58, v13, s24, v12
	v_mad_u32_u24 v59, v29, s24, v12
	v_mov_b32_e32 v28, 0
	v_mov_b32_e32 v29, v60
	v_mov_b32_e32 v25, v60
	v_mov_b32_e32 v26, v60
	v_mov_b32_e32 v27, v60
	v_mov_b32_e32 v20, 0
	v_mov_b32_e32 v21, v60
	v_mov_b32_e32 v22, v60
	v_mov_b32_e32 v23, v60
	v_mov_b32_e32 v12, 0
	v_mov_b32_e32 v13, v60
	v_mov_b32_e32 v14, v60
	v_mov_b32_e32 v15, v60

.LBB0_1811:
	s_and_b64 vcc, exec, s[6:7]
	s_cbranch_vccz .LBB0_1815
	s_lshl_b32 s6, s10, 3
	s_ashr_i32 s8, s10, 6
	v_mov_b32_e32 v12, v230
	s_and_b32 s6, s6, 0x180
	s_lshl_b32 s11, s8, 8
	s_lshl_b32 s7, s6, 1
	v_ashrrev_i32_e32 v1, 4, v12
	v_and_b32_e32 v13, 15, v12
	s_add_u32 s12, s43, s7
	v_add_u32_e32 v8, s11, v1
	s_addc_u32 s13, s20, 0
	v_lshlrev_b32_e32 v48, 4, v13
	v_ashrrev_i32_e32 v9, 31, v8
	v_lshl_add_u64 v[6:7], s[12:13], 0, v[48:49]
	v_lshlrev_b64 v[8:9], 10, v[8:9]
	v_lshl_add_u64 v[8:9], v[6:7], 0, v[8:9]
	s_waitcnt vmcnt(0) lgkmcnt(0)
	s_barrier
	global_load_dwordx4 v[112:115], v[8:9], off
	v_add_u32_e32 v4, 0, v48
	s_lshl_b32 s12, s8, 9
	s_or_b32 s12, s6, s12
	v_mad_u64_u32 v[14:15], s[14:15], v1, s24, v[4:5]
	v_ashrrev_i32_e32 v1, 5, v12
	v_lshlrev_b32_e32 v0, 4, v12
	v_and_b32_e32 v48, 0x1f0, v0
	v_lshl_add_u64 v[2:3], s[88:89], 0, v[48:49]
	v_add_u32_e32 v0, s23, v48
	v_readfirstlane_b32 s9, v12
	s_lshl_b32 s8, s8, 11
	s_ashr_i32 s9, s9, 2
	s_and_b32 s9, s9, -16
	v_bfe_u32 v54, v12, 4, 2
	s_lshl_b32 s90, s6, 2
	v_lshlrev_b32_e32 v48, 5, v54
	v_and_b32_e32 v30, 63, v12
	v_mov_b32_e32 v62, 0
	s_mov_b32 s7, 4
	v_mov_b32_e32 v63, 0xff800000
	v_mov_b32_e32 v44, 0
	v_mov_b32_e32 v45, v62
	v_mov_b32_e32 v46, v62
	v_mov_b32_e32 v47, v62
	v_mov_b32_e32 v40, 0
	v_mov_b32_e32 v41, v62
	v_mov_b32_e32 v42, v62
	v_mov_b32_e32 v43, v62
	v_mov_b32_e32 v36, 0
	v_mov_b32_e32 v37, v62
	v_mov_b32_e32 v38, v62
	v_mov_b32_e32 v39, v62
	v_mov_b32_e32 v31, v62
	v_mov_b32_e32 v32, 0
	v_mov_b32_e32 v33, v62
	v_mov_b32_e32 v34, v62
	v_mov_b32_e32 v35, v62
	v_add_u32_e32 v10, s12, v1
	v_ashrrev_i32_e32 v11, 31, v10
	v_lshlrev_b64 v[10:11], 9, v[10:11]
	v_lshl_add_u64 v[10:11], v[2:3], 0, v[10:11]
	global_load_dwordx4 v[144:147], v[10:11], off
	s_mov_b64 s[100:101], 0x8000
	s_mov_b64 s[98:99], 0x2000
	v_lshl_add_u64 v[8:9], v[8:9], 0, s[100:101]
	global_load_dwordx4 v[116:119], v[8:9], off
	v_lshl_add_u64 v[10:11], v[10:11], 0, s[98:99]
	global_load_dwordx4 v[148:151], v[10:11], off
	v_lshl_add_u64 v[8:9], v[8:9], 0, s[100:101]
	global_load_dwordx4 v[120:123], v[8:9], off
	v_lshl_add_u64 v[10:11], v[10:11], 0, s[98:99]
	global_load_dwordx4 v[152:155], v[10:11], off
	v_lshl_add_u64 v[8:9], v[8:9], 0, s[100:101]
	global_load_dwordx4 v[124:127], v[8:9], off
	v_lshl_add_u64 v[10:11], v[10:11], 0, s[98:99]
	global_load_dwordx4 v[156:159], v[10:11], off
	v_lshl_add_u64 v[8:9], v[8:9], 0, s[100:101]
	global_load_dwordx4 v[128:131], v[8:9], off
	v_lshl_add_u64 v[10:11], v[10:11], 0, s[98:99]
	global_load_dwordx4 v[160:163], v[10:11], off
	v_lshl_add_u64 v[8:9], v[8:9], 0, s[100:101]
	global_load_dwordx4 v[132:135], v[8:9], off
	v_lshl_add_u64 v[10:11], v[10:11], 0, s[98:99]
	global_load_dwordx4 v[164:167], v[10:11], off
	v_lshl_add_u64 v[8:9], v[8:9], 0, s[100:101]
	global_load_dwordx4 v[136:139], v[8:9], off
	v_lshl_add_u64 v[10:11], v[10:11], 0, s[98:99]
	global_load_dwordx4 v[168:171], v[10:11], off
	v_lshl_add_u64 v[8:9], v[8:9], 0, s[100:101]
	global_load_dwordx4 v[140:143], v[8:9], off
	v_lshl_add_u64 v[10:11], v[10:11], 0, s[98:99]
	global_load_dwordx4 v[172:175], v[10:11], off
	v_mad_u32_u24 v5, v1, s26, v0
	s_lshl_b32 s11, s10, 7
	s_and_b32 s11, s11, 0x780
	s_or_b32 s8, s11, s8
	v_or_b32_e32 v0, s8, v13
	v_add_u32_e32 v50, s9, v0
	v_ashrrev_i32_e32 v51, 31, v50
	v_lshlrev_b64 v[0:1], 11, v[50:51]
	v_lshl_add_u64 v[0:1], s[84:85], 0, v[0:1]
	v_lshl_add_u64 v[0:1], v[0:1], 0, s[90:91]
	v_lshl_add_u64 v[26:27], v[0:1], 0, v[48:49]
	v_add_co_u32_e32 v28, vcc, s25, v26
	s_nop 0
	s_nop 0
	v_addc_co_u32_e32 v29, vcc, 0, v27, vcc
	global_load_dwordx4 v[176:179], v[26:27], off offset:16
	global_load_dwordx4 v[180:183], v[26:27], off offset:0
	global_load_dwordx4 v[184:187], v[28:29], off offset:0
	v_lshl_add_u64 v[6:7], v[26:27], 0, s[92:93]
	global_load_dwordx4 v[188:191], v[6:7], off offset:16
	global_load_dwordx4 v[192:195], v[26:27], off offset:144
	global_load_dwordx4 v[196:199], v[26:27], off offset:128
	global_load_dwordx4 v[200:203], v[28:29], off offset:128
	v_lshl_add_u64 v[6:7], v[26:27], 0, s[94:95]
	global_load_dwordx4 v[204:207], v[6:7], off offset:16
	global_load_dwordx4 v[208:211], v[26:27], off offset:272
	global_load_dwordx4 v[212:215], v[26:27], off offset:256
	global_load_dwordx4 v[216:219], v[28:29], off offset:256
	v_lshl_add_u64 v[6:7], v[26:27], 0, s[2:3]
	global_load_dwordx4 v[220:223], v[6:7], off offset:16
	global_load_dwordx4 v[224:227], v[26:27], off offset:400
	global_load_dwordx4 v[232:235], v[26:27], off offset:384
	global_load_dwordx4 v[236:239], v[28:29], off offset:384
	v_lshl_add_u64 v[6:7], v[26:27], 0, s[4:5]
	global_load_dwordx4 v[240:243], v[6:7], off offset:16
	s_waitcnt vmcnt(31)
	ds_write_b128 v14, v[112:115]
	s_waitcnt vmcnt(30)
	ds_write_b128 v5, v[144:147]
	s_waitcnt vmcnt(29)
	ds_write_b128 v14, v[116:119] offset:8704
	s_waitcnt vmcnt(28)
	ds_write_b128 v5, v[148:151] offset:8448
	s_waitcnt vmcnt(27)
	ds_write_b128 v14, v[120:123] offset:17408
	s_waitcnt vmcnt(26)
	ds_write_b128 v5, v[152:155] offset:16896
	s_waitcnt vmcnt(25)
	ds_write_b128 v14, v[124:127] offset:26112
	s_waitcnt vmcnt(24)
	ds_write_b128 v5, v[156:159] offset:25344
	s_waitcnt vmcnt(23)
	ds_write_b128 v14, v[128:131] offset:34816
	s_waitcnt vmcnt(22)
	ds_write_b128 v5, v[160:163] offset:33792
	s_waitcnt vmcnt(21)
	ds_write_b128 v14, v[132:135] offset:43520
	s_waitcnt vmcnt(20)
	ds_write_b128 v5, v[164:167] offset:42240
	s_waitcnt vmcnt(19)
	ds_write_b128 v14, v[136:139] offset:52224
	s_waitcnt vmcnt(18)
	ds_write_b128 v5, v[168:171] offset:50688
	s_waitcnt vmcnt(17)
	ds_write_b128 v14, v[140:143] offset:60928
	s_waitcnt vmcnt(16)
	ds_write_b128 v5, v[172:175] offset:59136
	s_waitcnt lgkmcnt(0)
	s_barrier
	s_waitcnt vmcnt(0)
	v_pk_add_f32 v[180:181], v[180:181], v[184:185]
	v_pk_add_f32 v[182:183], v[182:183], v[186:187]
	v_pk_add_f32 v[176:177], v[176:177], v[188:189]
	v_pk_add_f32 v[178:179], v[178:179], v[190:191]
	v_cvt_pk_bf16_f32 v0, v180, v181
	v_cvt_pk_bf16_f32 v1, v182, v183
	v_cvt_pk_bf16_f32 v2, v176, v177
	v_cvt_pk_bf16_f32 v3, v178, v179
	v_pk_add_f32 v[196:197], v[196:197], v[200:201]
	v_pk_add_f32 v[198:199], v[198:199], v[202:203]
	v_pk_add_f32 v[192:193], v[192:193], v[204:205]
	v_pk_add_f32 v[194:195], v[194:195], v[206:207]
	v_cvt_pk_bf16_f32 v4, v196, v197
	v_cvt_pk_bf16_f32 v5, v198, v199
	v_cvt_pk_bf16_f32 v6, v192, v193
	v_cvt_pk_bf16_f32 v7, v194, v195
	v_pk_add_f32 v[212:213], v[212:213], v[216:217]
	v_pk_add_f32 v[214:215], v[214:215], v[218:219]
	v_pk_add_f32 v[208:209], v[208:209], v[220:221]
	v_pk_add_f32 v[210:211], v[210:211], v[222:223]
	v_cvt_pk_bf16_f32 v8, v212, v213
	v_cvt_pk_bf16_f32 v9, v214, v215
	v_cvt_pk_bf16_f32 v10, v208, v209
	v_cvt_pk_bf16_f32 v11, v210, v211
	v_pk_add_f32 v[232:233], v[232:233], v[236:237]
	v_pk_add_f32 v[234:235], v[234:235], v[238:239]
	v_pk_add_f32 v[224:225], v[224:225], v[240:241]
	v_pk_add_f32 v[226:227], v[226:227], v[242:243]
	v_cvt_pk_bf16_f32 v16, v232, v233
	v_cvt_pk_bf16_f32 v17, v234, v235
	v_cvt_pk_bf16_f32 v18, v224, v225
	v_cvt_pk_bf16_f32 v19, v226, v227
	v_and_b32_e32 v21, 64, v53
	v_xor_b32_e32 v20, 16, v53
	v_add_u32_e32 v21, 64, v21
	v_cmp_lt_i32_e32 vcc, v20, v21
	s_nop 1
	v_cndmask_b32_e32 v20, v53, v20, vcc
	v_lshlrev_b32_e32 v48, 2, v20
	v_xor_b32_e32 v20, 32, v53
	v_cmp_lt_i32_e32 vcc, v20, v21
	s_nop 1
	v_and_b32_e32 v14, 48, v12
	v_cndmask_b32_e32 v20, v53, v20, vcc
	v_lshrrev_b32_e32 v12, 1, v12
	v_or_b32_e32 v15, 48, v30
	v_lshlrev_b32_e32 v55, 2, v20
	v_and_b32_e32 v12, 24, v12
	v_or_b32_e32 v20, 0x70, v30
	v_mad_u32_u24 v56, v20, s26, v12
	v_mad_u32_u24 v57, v15, s26, v12
	v_mad_u32_u24 v58, v13, s26, v12
	v_mad_u32_u24 v59, v15, s24, v14
	v_mad_u32_u24 v60, v13, s24, v14
	v_mov_b32_e32 v28, 0
	v_mov_b32_e32 v29, v62
	v_mov_b32_e32 v30, v62
	v_mov_b32_e32 v24, 0
	v_mov_b32_e32 v25, v62
	v_mov_b32_e32 v26, v62
	v_mov_b32_e32 v27, v62
	v_mov_b32_e32 v20, 0
	v_mov_b32_e32 v21, v62
	v_mov_b32_e32 v22, v62
	v_mov_b32_e32 v23, v62
	v_mov_b32_e32 v12, 0
	v_mov_b32_e32 v13, v62
	v_mov_b32_e32 v14, v62
	v_mov_b32_e32 v15, v62
